# gemm_resid epilogues: residual loads issued 8 at a time into free fragment registers with one wait instead of vmcnt(0) after each load
# baseline (speedup 1.0000x reference)
.LBB0_32:
	s_add_i32 s11, s10, 2
	ds_read_b128 v[132:135], v159
	ds_read_b128 v[136:139], v160
	ds_read_b128 v[180:183], v161
	ds_read_b128 v[184:187], v162
	s_cmpk_lt_u32 s10, 0x56
	s_cselect_b32 s12, s8, s5
	s_cselect_b32 s13, s7, s6
	s_cselect_b32 s14, s9, 0
	s_mulk_i32 s13, 0x1600
	s_mulk_i32 s12, 0x1600
	s_or_b32 s15, s14, 64
	s_add_i32 s17, s12, s14
	s_add_i32 s18, s13, 0xb0000
	s_add_i32 s16, s13, s14
	s_add_i32 s13, s15, s13
	s_add_i32 s12, s15, s12
	s_lshl_b32 s17, s17, 1
	s_add_i32 s14, s18, s14
	s_add_i32 s18, s18, s15
	s_addk_i32 s9, 0x80
	s_lshl_b32 s16, s16, 1
	s_lshl_b32 s19, s13, 1
	s_lshl_b32 s13, s12, 1
	s_lshl_b32 s14, s14, 1
	s_add_i32 s15, s17, 0x160000
	s_lshl_b32 s12, s18, 1
	s_cmpk_gt_u32 s10, 0x55
	v_readfirstlane_b32 s10, v163
	v_add_u32_e32 v131, 0xfff50000, v130
	s_mov_b32 m0, s10
	v_readfirstlane_b32 s10, v165
	ds_read_b128 v[188:191], v157
	ds_read_b128 v[192:195], v157 offset:1024
	ds_read_b128 v[196:199], v157 offset:2048
	ds_read_b128 v[200:203], v157 offset:3072
	ds_read_b128 v[204:207], v157 offset:4096
	ds_read_b128 v[208:211], v157 offset:5120
	ds_read_b128 v[212:215], v157 offset:6144
	ds_read_b128 v[216:219], v157 offset:7168
	global_load_lds_dwordx4 v131, s[76:77]
	s_mov_b32 m0, s10
	s_nop 0
	global_load_lds_dwordx4 v130, s[76:77]
	s_waitcnt lgkmcnt(8)
	s_barrier
	s_waitcnt lgkmcnt(0)
	s_setprio 1
	s_waitcnt lgkmcnt(0)
	v_mfma_f32_16x16x32_bf16 v[126:129], v[132:135], v[188:191], v[126:129]
	v_mfma_f32_16x16x32_bf16 v[122:125], v[180:183], v[188:191], v[122:125]
	v_mfma_f32_16x16x32_bf16 v[118:121], v[132:135], v[196:199], v[118:121]
	v_mfma_f32_16x16x32_bf16 v[114:117], v[180:183], v[196:199], v[114:117]
	v_mfma_f32_16x16x32_bf16 v[110:113], v[132:135], v[204:207], v[110:113]
	v_mfma_f32_16x16x32_bf16 v[106:109], v[180:183], v[204:207], v[106:109]
	v_mfma_f32_16x16x32_bf16 v[102:105], v[132:135], v[212:215], v[102:105]
	v_mfma_f32_16x16x32_bf16 v[98:101], v[180:183], v[212:215], v[98:101]
	v_mfma_f32_16x16x32_bf16 v[126:129], v[136:139], v[192:195], v[126:129]
	v_mfma_f32_16x16x32_bf16 v[122:125], v[184:187], v[192:195], v[122:125]
	v_mfma_f32_16x16x32_bf16 v[118:121], v[136:139], v[200:203], v[118:121]
	v_mfma_f32_16x16x32_bf16 v[114:117], v[184:187], v[200:203], v[114:117]
	v_mfma_f32_16x16x32_bf16 v[110:113], v[136:139], v[208:211], v[110:113]
	v_mfma_f32_16x16x32_bf16 v[106:109], v[184:187], v[208:211], v[106:109]
	v_mfma_f32_16x16x32_bf16 v[102:105], v[136:139], v[216:219], v[102:105]
	v_mfma_f32_16x16x32_bf16 v[98:101], v[184:187], v[216:219], v[98:101]
	s_setprio 0
	s_barrier
	v_readfirstlane_b32 s10, v144
	v_add_u32_e32 v131, s16, v142
	s_mov_b32 m0, s10
	v_readfirstlane_b32 s10, v145
	ds_read_b128 v[220:223], v166
	ds_read_b128 v[242:245], v167
	ds_read_b128 v[246:249], v168
	ds_read_b128 v[250:253], v169
	global_load_lds_dwordx4 v131, s[78:79]
	v_add_u32_e32 v131, s16, v143
	s_mov_b32 m0, s10
	s_nop 0
	global_load_lds_dwordx4 v131, s[78:79]
	s_barrier
	s_waitcnt lgkmcnt(0)
	s_setprio 1
	s_waitcnt lgkmcnt(0)
	v_mfma_f32_16x16x32_bf16 v[94:97], v[220:223], v[188:191], v[94:97]
	v_mfma_f32_16x16x32_bf16 v[90:93], v[246:249], v[188:191], v[90:93]
	v_mfma_f32_16x16x32_bf16 v[86:89], v[220:223], v[196:199], v[86:89]
	v_mfma_f32_16x16x32_bf16 v[82:85], v[246:249], v[196:199], v[82:85]
	v_mfma_f32_16x16x32_bf16 v[78:81], v[220:223], v[204:207], v[78:81]
	v_mfma_f32_16x16x32_bf16 v[74:77], v[246:249], v[204:207], v[74:77]
	v_mfma_f32_16x16x32_bf16 v[70:73], v[220:223], v[212:215], v[70:73]
	v_mfma_f32_16x16x32_bf16 v[66:69], v[246:249], v[212:215], v[66:69]
	v_mfma_f32_16x16x32_bf16 v[94:97], v[242:245], v[192:195], v[94:97]
	v_mfma_f32_16x16x32_bf16 v[90:93], v[250:253], v[192:195], v[90:93]
	v_mfma_f32_16x16x32_bf16 v[86:89], v[242:245], v[200:203], v[86:89]
	v_mfma_f32_16x16x32_bf16 v[82:85], v[250:253], v[200:203], v[82:85]
	v_mfma_f32_16x16x32_bf16 v[78:81], v[242:245], v[208:211], v[78:81]
	v_mfma_f32_16x16x32_bf16 v[74:77], v[250:253], v[208:211], v[74:77]
	v_mfma_f32_16x16x32_bf16 v[70:73], v[242:245], v[216:219], v[70:73]
	v_mfma_f32_16x16x32_bf16 v[66:69], v[250:253], v[216:219], v[66:69]
	s_setprio 0
	v_readfirstlane_b32 s10, v0
	v_add_u32_e32 v131, s17, v142
	s_mov_b32 m0, s10
	v_readfirstlane_b32 s10, v146
	s_barrier
	ds_read_b128 v[188:191], v157 offset:16384
	ds_read_b128 v[192:195], v157 offset:17408
	ds_read_b128 v[196:199], v157 offset:18432
	ds_read_b128 v[200:203], v157 offset:19456
	ds_read_b128 v[204:207], v157 offset:20480
	ds_read_b128 v[208:211], v157 offset:21504
	ds_read_b128 v[212:215], v157 offset:22528
	ds_read_b128 v[216:219], v157 offset:23552
	global_load_lds_dwordx4 v131, s[76:77]
	v_add_u32_e32 v131, s17, v143
	s_mov_b32 m0, s10
	s_nop 0
	global_load_lds_dwordx4 v131, s[76:77]
	s_barrier
	s_waitcnt lgkmcnt(0)
	s_setprio 1
	s_waitcnt lgkmcnt(0)
	v_mfma_f32_16x16x32_bf16 v[62:65], v[132:135], v[188:191], v[62:65]
	v_mfma_f32_16x16x32_bf16 v[58:61], v[180:183], v[188:191], v[58:61]
	v_mfma_f32_16x16x32_bf16 v[54:57], v[132:135], v[196:199], v[54:57]
	v_mfma_f32_16x16x32_bf16 v[50:53], v[180:183], v[196:199], v[50:53]
	v_mfma_f32_16x16x32_bf16 v[46:49], v[132:135], v[204:207], v[46:49]
	v_mfma_f32_16x16x32_bf16 v[42:45], v[180:183], v[204:207], v[42:45]
	v_mfma_f32_16x16x32_bf16 v[38:41], v[132:135], v[212:215], v[38:41]
	v_mfma_f32_16x16x32_bf16 v[34:37], v[180:183], v[212:215], v[34:37]
	v_mfma_f32_16x16x32_bf16 v[62:65], v[136:139], v[192:195], v[62:65]
	v_mfma_f32_16x16x32_bf16 v[58:61], v[184:187], v[192:195], v[58:61]
	v_mfma_f32_16x16x32_bf16 v[54:57], v[136:139], v[200:203], v[54:57]
	v_mfma_f32_16x16x32_bf16 v[50:53], v[184:187], v[200:203], v[50:53]
	v_mfma_f32_16x16x32_bf16 v[46:49], v[136:139], v[208:211], v[46:49]
	v_mfma_f32_16x16x32_bf16 v[42:45], v[184:187], v[208:211], v[42:45]
	v_mfma_f32_16x16x32_bf16 v[38:41], v[136:139], v[216:219], v[38:41]
	v_mfma_f32_16x16x32_bf16 v[34:37], v[184:187], v[216:219], v[34:37]
	s_setprio 0
	s_barrier
	v_readfirstlane_b32 s10, v147
	v_add_u32_e32 v131, s14, v142
	s_mov_b32 m0, s10
	v_readfirstlane_b32 s10, v148
	global_load_lds_dwordx4 v131, s[78:79]
	v_add_u32_e32 v131, s14, v143
	s_mov_b32 m0, s10
	s_nop 0
	global_load_lds_dwordx4 v131, s[78:79]
	s_waitcnt vmcnt(6)
	s_barrier
	s_setprio 1
	v_mfma_f32_16x16x32_bf16 v[30:33], v[220:223], v[188:191], v[30:33]
	v_mfma_f32_16x16x32_bf16 v[26:29], v[246:249], v[188:191], v[26:29]
	v_mfma_f32_16x16x32_bf16 v[22:25], v[220:223], v[196:199], v[22:25]
	v_mfma_f32_16x16x32_bf16 v[18:21], v[246:249], v[196:199], v[18:21]
	v_mfma_f32_16x16x32_bf16 v[14:17], v[220:223], v[204:207], v[14:17]
	v_mfma_f32_16x16x32_bf16 v[10:13], v[246:249], v[204:207], v[10:13]
	v_mfma_f32_16x16x32_bf16 v[6:9], v[220:223], v[212:215], v[6:9]
	v_mfma_f32_16x16x32_bf16 v[2:5], v[246:249], v[212:215], v[2:5]
	v_mfma_f32_16x16x32_bf16 v[30:33], v[242:245], v[192:195], v[30:33]
	v_mfma_f32_16x16x32_bf16 v[26:29], v[250:253], v[192:195], v[26:29]
	v_mfma_f32_16x16x32_bf16 v[22:25], v[242:245], v[200:203], v[22:25]
	v_mfma_f32_16x16x32_bf16 v[18:21], v[250:253], v[200:203], v[18:21]
	v_mfma_f32_16x16x32_bf16 v[14:17], v[242:245], v[208:211], v[14:17]
	v_mfma_f32_16x16x32_bf16 v[10:13], v[250:253], v[208:211], v[10:13]
	v_mfma_f32_16x16x32_bf16 v[6:9], v[242:245], v[216:219], v[6:9]
	v_mfma_f32_16x16x32_bf16 v[2:5], v[250:253], v[216:219], v[2:5]
	s_setprio 0
	s_barrier
	ds_read_b128 v[132:135], v170
	ds_read_b128 v[136:139], v171
	ds_read_b128 v[180:183], v172
	ds_read_b128 v[184:187], v173
	v_readfirstlane_b32 s10, v149
	v_add_u32_e32 v131, s15, v142
	s_mov_b32 m0, s10
	v_readfirstlane_b32 s10, v150
	ds_read_b128 v[188:191], v157 offset:32768
	ds_read_b128 v[192:195], v157 offset:33792
	ds_read_b128 v[196:199], v157 offset:34816
	ds_read_b128 v[200:203], v157 offset:35840
	ds_read_b128 v[204:207], v157 offset:36864
	ds_read_b128 v[208:211], v157 offset:37888
	ds_read_b128 v[212:215], v157 offset:38912
	ds_read_b128 v[216:219], v157 offset:39936
	global_load_lds_dwordx4 v131, s[76:77]
	v_add_u32_e32 v131, s15, v143
	s_mov_b32 m0, s10
	s_nop 0
	global_load_lds_dwordx4 v131, s[76:77]
	s_waitcnt lgkmcnt(8)
	s_barrier
	s_waitcnt lgkmcnt(0)
	s_setprio 1
	s_waitcnt lgkmcnt(0)
	v_mfma_f32_16x16x32_bf16 v[126:129], v[132:135], v[188:191], v[126:129]
	v_mfma_f32_16x16x32_bf16 v[122:125], v[180:183], v[188:191], v[122:125]
	v_mfma_f32_16x16x32_bf16 v[118:121], v[132:135], v[196:199], v[118:121]
	v_mfma_f32_16x16x32_bf16 v[114:117], v[180:183], v[196:199], v[114:117]
	v_mfma_f32_16x16x32_bf16 v[110:113], v[132:135], v[204:207], v[110:113]
	v_mfma_f32_16x16x32_bf16 v[106:109], v[180:183], v[204:207], v[106:109]
	v_mfma_f32_16x16x32_bf16 v[102:105], v[132:135], v[212:215], v[102:105]
	v_mfma_f32_16x16x32_bf16 v[98:101], v[180:183], v[212:215], v[98:101]
	v_mfma_f32_16x16x32_bf16 v[126:129], v[136:139], v[192:195], v[126:129]
	v_mfma_f32_16x16x32_bf16 v[122:125], v[184:187], v[192:195], v[122:125]
	v_mfma_f32_16x16x32_bf16 v[118:121], v[136:139], v[200:203], v[118:121]
	v_mfma_f32_16x16x32_bf16 v[114:117], v[184:187], v[200:203], v[114:117]
	v_mfma_f32_16x16x32_bf16 v[110:113], v[136:139], v[208:211], v[110:113]
	v_mfma_f32_16x16x32_bf16 v[106:109], v[184:187], v[208:211], v[106:109]
	v_mfma_f32_16x16x32_bf16 v[102:105], v[136:139], v[216:219], v[102:105]
	v_mfma_f32_16x16x32_bf16 v[98:101], v[184:187], v[216:219], v[98:101]
	s_setprio 0
	s_barrier
	v_readfirstlane_b32 s10, v151
	v_add_u32_e32 v131, s19, v142
	s_mov_b32 m0, s10
	v_readfirstlane_b32 s10, v152
	ds_read_b128 v[220:223], v174
	ds_read_b128 v[242:245], v175
	ds_read_b128 v[246:249], v176
	ds_read_b128 v[250:253], v177
	global_load_lds_dwordx4 v131, s[78:79]
	v_add_u32_e32 v131, s19, v143
	s_mov_b32 m0, s10
	s_nop 0
	global_load_lds_dwordx4 v131, s[78:79]
	s_barrier
	s_waitcnt lgkmcnt(0)
	s_setprio 1
	s_waitcnt lgkmcnt(0)
	v_mfma_f32_16x16x32_bf16 v[94:97], v[220:223], v[188:191], v[94:97]
	v_mfma_f32_16x16x32_bf16 v[90:93], v[246:249], v[188:191], v[90:93]
	v_mfma_f32_16x16x32_bf16 v[86:89], v[220:223], v[196:199], v[86:89]
	v_mfma_f32_16x16x32_bf16 v[82:85], v[246:249], v[196:199], v[82:85]
	v_mfma_f32_16x16x32_bf16 v[78:81], v[220:223], v[204:207], v[78:81]
	v_mfma_f32_16x16x32_bf16 v[74:77], v[246:249], v[204:207], v[74:77]
	v_mfma_f32_16x16x32_bf16 v[70:73], v[220:223], v[212:215], v[70:73]
	v_mfma_f32_16x16x32_bf16 v[66:69], v[246:249], v[212:215], v[66:69]
	v_mfma_f32_16x16x32_bf16 v[94:97], v[242:245], v[192:195], v[94:97]
	v_mfma_f32_16x16x32_bf16 v[90:93], v[250:253], v[192:195], v[90:93]
	v_mfma_f32_16x16x32_bf16 v[86:89], v[242:245], v[200:203], v[86:89]
	v_mfma_f32_16x16x32_bf16 v[82:85], v[250:253], v[200:203], v[82:85]
	v_mfma_f32_16x16x32_bf16 v[78:81], v[242:245], v[208:211], v[78:81]
	v_mfma_f32_16x16x32_bf16 v[74:77], v[250:253], v[208:211], v[74:77]
	v_mfma_f32_16x16x32_bf16 v[70:73], v[242:245], v[216:219], v[70:73]
	v_mfma_f32_16x16x32_bf16 v[66:69], v[250:253], v[216:219], v[66:69]
	s_setprio 0
	v_readfirstlane_b32 s10, v153
	v_add_u32_e32 v131, s13, v142
	s_mov_b32 m0, s10
	v_readfirstlane_b32 s10, v154
	s_barrier
	ds_read_b128 v[188:191], v157 offset:49152
	ds_read_b128 v[192:195], v157 offset:50176
	ds_read_b128 v[196:199], v157 offset:51200
	ds_read_b128 v[200:203], v157 offset:52224
	ds_read_b128 v[204:207], v157 offset:53248
	ds_read_b128 v[208:211], v157 offset:54272
	ds_read_b128 v[212:215], v157 offset:55296
	ds_read_b128 v[216:219], v157 offset:56320
	global_load_lds_dwordx4 v131, s[76:77]
	v_add_u32_e32 v131, s13, v143
	s_mov_b32 m0, s10
	s_nop 0
	global_load_lds_dwordx4 v131, s[76:77]
	s_barrier
; #define EPI_SCHED __builtin_amdgcn_sched_barrier(0)
; DI void gemm_resid(const u16* A, const u16* Bt, int K, const float* xin, float* xout, int bid, int nb, int tid) {
;     ...
; #pragma unroll
;     for (int ai = 0; ai < 2; ++ai)
; #pragma unroll
;       for (int bj = 0; bj < 2; ++bj) {
;         float4 xi[4][2];
; #pragma unroll
;         for (int m = 0; m < 4; ++m)
; #pragma unroll
;           for (int n = 0; n < 2; ++n) xi[m][n] = *reinterpret_cast<const float4*>(xin + (size_t)ACC_ROW * 2048 + ACC_COL);
; #pragma unroll
;         for (int m = 0; m < 4; ++m)
; #pragma unroll
;           for (int n = 0; n < 2; ++n) {
;             const f32x4 v = acc[ai][bj][m][n];
;             float4 r; r.x = xi[m][n].x + v[0]; r.y = xi[m][n].y + v[1]; r.z = xi[m][n].z + v[2]; r.w = xi[m][n].w + v[3];
;             *reinterpret_cast<float4*>(xout + (size_t)ACC_ROW * 2048 + ACC_COL) = r;
;           }
;         EPI_SCHED;
;       }
	s_waitcnt lgkmcnt(0)
	s_setprio 1
	s_waitcnt lgkmcnt(0)
	v_mfma_f32_16x16x32_bf16 v[62:65], v[132:135], v[188:191], v[62:65]
	v_mfma_f32_16x16x32_bf16 v[58:61], v[180:183], v[188:191], v[58:61]
	v_mfma_f32_16x16x32_bf16 v[54:57], v[132:135], v[196:199], v[54:57]
	v_mfma_f32_16x16x32_bf16 v[50:53], v[180:183], v[196:199], v[50:53]
	v_mfma_f32_16x16x32_bf16 v[46:49], v[132:135], v[204:207], v[46:49]
	v_mfma_f32_16x16x32_bf16 v[42:45], v[180:183], v[204:207], v[42:45]
	v_mfma_f32_16x16x32_bf16 v[38:41], v[132:135], v[212:215], v[38:41]
	v_mfma_f32_16x16x32_bf16 v[34:37], v[180:183], v[212:215], v[34:37]
	v_mfma_f32_16x16x32_bf16 v[62:65], v[136:139], v[192:195], v[62:65]
	v_mfma_f32_16x16x32_bf16 v[58:61], v[184:187], v[192:195], v[58:61]
	v_mfma_f32_16x16x32_bf16 v[54:57], v[136:139], v[200:203], v[54:57]
	v_mfma_f32_16x16x32_bf16 v[50:53], v[184:187], v[200:203], v[50:53]
	v_mfma_f32_16x16x32_bf16 v[46:49], v[136:139], v[208:211], v[46:49]
	v_mfma_f32_16x16x32_bf16 v[42:45], v[184:187], v[208:211], v[42:45]
	v_mfma_f32_16x16x32_bf16 v[38:41], v[136:139], v[216:219], v[38:41]
	v_mfma_f32_16x16x32_bf16 v[34:37], v[184:187], v[216:219], v[34:37]
	s_setprio 0
	s_barrier
	v_readfirstlane_b32 s10, v155
	v_add_u32_e32 v131, s12, v142
	s_mov_b32 m0, s10
	v_readfirstlane_b32 s10, v156
	global_load_lds_dwordx4 v131, s[78:79]
	v_add_u32_e32 v131, s12, v143
	s_mov_b32 m0, s10
	s_nop 0
	global_load_lds_dwordx4 v131, s[78:79]
	s_waitcnt vmcnt(6)
	s_barrier
	s_setprio 1
	v_mfma_f32_16x16x32_bf16 v[30:33], v[220:223], v[188:191], v[30:33]
	v_mfma_f32_16x16x32_bf16 v[26:29], v[246:249], v[188:191], v[26:29]
	v_mfma_f32_16x16x32_bf16 v[22:25], v[220:223], v[196:199], v[22:25]
	v_mfma_f32_16x16x32_bf16 v[18:21], v[246:249], v[196:199], v[18:21]
	v_mfma_f32_16x16x32_bf16 v[14:17], v[220:223], v[204:207], v[14:17]
	v_mfma_f32_16x16x32_bf16 v[10:13], v[246:249], v[204:207], v[10:13]
	v_mfma_f32_16x16x32_bf16 v[6:9], v[220:223], v[212:215], v[6:9]
	v_mfma_f32_16x16x32_bf16 v[2:5], v[246:249], v[212:215], v[2:5]
	v_mfma_f32_16x16x32_bf16 v[30:33], v[242:245], v[192:195], v[30:33]
	v_mfma_f32_16x16x32_bf16 v[26:29], v[250:253], v[192:195], v[26:29]
	v_mfma_f32_16x16x32_bf16 v[22:25], v[242:245], v[200:203], v[22:25]
	v_mfma_f32_16x16x32_bf16 v[18:21], v[250:253], v[200:203], v[18:21]
	v_mfma_f32_16x16x32_bf16 v[14:17], v[242:245], v[208:211], v[14:17]
	v_mfma_f32_16x16x32_bf16 v[10:13], v[250:253], v[208:211], v[10:13]
	v_mfma_f32_16x16x32_bf16 v[6:9], v[242:245], v[216:219], v[6:9]
	v_mfma_f32_16x16x32_bf16 v[2:5], v[250:253], v[216:219], v[2:5]
	s_setprio 0
	v_add_u32_e32 v130, 0x100, v130
	s_mov_b32 s10, s11
	s_barrier
	s_cbranch_scc0 .LBB0_32
	v_mov_b32_e32 v131, v239
	s_nop 0
	v_ashrrev_i32_e32 v130, 2, v131
	v_and_b32_e32 v130, 0xffffffc0, v130
	v_and_or_b32 v132, v131, 15, s8
	v_add_u32_e32 v130, v132, v130
	v_lshrrev_b32_e32 v132, 1, v131
	v_lshrrev_b32_e32 v131, 2, v131
	v_and_b32_e32 v132, 0x60, v132
	v_and_b32_e32 v131, 12, v131
	v_or3_b32 v132, v132, v131, s7
	v_ashrrev_i32_e32 v131, 31, v130
	v_ashrrev_i32_e32 v133, 31, v132
	v_lshlrev_b64 v[134:135], 13, v[130:131]
	v_lshl_add_u64 v[134:135], s[72:73], 0, v[134:135]
	v_lshlrev_b64 v[132:133], 2, v[132:133]
	v_lshl_add_u64 v[140:141], v[134:135], 0, v[132:133]
	v_or_b32_e32 v134, 16, v130
	v_ashrrev_i32_e32 v135, 31, v134
	v_lshlrev_b64 v[134:135], 13, v[134:135]
	v_lshl_add_u64 v[134:135], s[72:73], 0, v[134:135]
	v_lshl_add_u64 v[138:139], v[134:135], 0, v[132:133]
	v_or_b32_e32 v134, 32, v130
	v_ashrrev_i32_e32 v135, 31, v134
	v_lshlrev_b64 v[134:135], 13, v[134:135]
	v_lshl_add_u64 v[134:135], s[72:73], 0, v[134:135]
	v_lshl_add_u64 v[136:137], v[134:135], 0, v[132:133]
	v_or_b32_e32 v134, 48, v130
	v_ashrrev_i32_e32 v135, 31, v134
	v_lshlrev_b64 v[134:135], 13, v[134:135]
	v_lshl_add_u64 v[134:135], s[72:73], 0, v[134:135]
	v_lshl_add_u64 v[134:135], v[134:135], 0, v[132:133]
	global_load_dwordx4 v[180:183], v[140:141], off
	global_load_dwordx4 v[184:187], v[140:141], off offset:64
	global_load_dwordx4 v[188:191], v[138:139], off
	global_load_dwordx4 v[192:195], v[138:139], off offset:64
	global_load_dwordx4 v[196:199], v[136:137], off
	global_load_dwordx4 v[200:203], v[136:137], off offset:64
	global_load_dwordx4 v[204:207], v[134:135], off
	global_load_dwordx4 v[208:211], v[134:135], off offset:64
	s_waitcnt vmcnt(0)
	v_pk_add_f32 v[126:127], v[126:127], v[180:181]
	v_pk_add_f32 v[128:129], v[128:129], v[182:183]
	global_store_dwordx4 v[140:141], v[126:129], off
	v_pk_add_f32 v[122:123], v[122:123], v[184:185]
	v_pk_add_f32 v[124:125], v[124:125], v[186:187]
	global_store_dwordx4 v[140:141], v[122:125], off offset:64
	v_pk_add_f32 v[118:119], v[118:119], v[188:189]
	v_pk_add_f32 v[120:121], v[120:121], v[190:191]
	global_store_dwordx4 v[138:139], v[118:121], off
	v_pk_add_f32 v[114:115], v[114:115], v[192:193]
	v_pk_add_f32 v[116:117], v[116:117], v[194:195]
	global_store_dwordx4 v[138:139], v[114:117], off offset:64
	v_pk_add_f32 v[110:111], v[110:111], v[196:197]
	v_pk_add_f32 v[112:113], v[112:113], v[198:199]
	global_store_dwordx4 v[136:137], v[110:113], off
	v_pk_add_f32 v[106:107], v[106:107], v[200:201]
	v_pk_add_f32 v[108:109], v[108:109], v[202:203]
	global_store_dwordx4 v[136:137], v[106:109], off offset:64
	v_pk_add_f32 v[102:103], v[102:103], v[204:205]
	v_pk_add_f32 v[104:105], v[104:105], v[206:207]
	global_store_dwordx4 v[134:135], v[102:105], off
	v_pk_add_f32 v[98:99], v[98:99], v[208:209]
	v_pk_add_f32 v[100:101], v[100:101], v[210:211]
	global_store_dwordx4 v[134:135], v[98:101], off offset:64
	global_load_dwordx4 v[180:183], v[140:141], off offset:512
	global_load_dwordx4 v[184:187], v[140:141], off offset:576
	global_load_dwordx4 v[188:191], v[138:139], off offset:512
	global_load_dwordx4 v[192:195], v[138:139], off offset:576
	global_load_dwordx4 v[196:199], v[136:137], off offset:512
	global_load_dwordx4 v[200:203], v[136:137], off offset:576
	global_load_dwordx4 v[204:207], v[134:135], off offset:512
	global_load_dwordx4 v[208:211], v[134:135], off offset:576
	s_waitcnt vmcnt(0)
; #define EPI_SCHED __builtin_amdgcn_sched_barrier(0)
; DI void gemm_resid(const u16* A, const u16* Bt, int K, const float* xin, float* xout, int bid, int nb, int tid) {
;     ...
;     for (int ai = 0; ai < 2; ++ai)
; #pragma unroll
;       for (int bj = 0; bj < 2; ++bj) {
;         float4 xi[4][2];
; #pragma unroll
;         for (int m = 0; m < 4; ++m)
; #pragma unroll
;           for (int n = 0; n < 2; ++n) xi[m][n] = *reinterpret_cast<const float4*>(xin + (size_t)ACC_ROW * 2048 + ACC_COL);
; #pragma unroll
;         for (int m = 0; m < 4; ++m)
; #pragma unroll
;           for (int n = 0; n < 2; ++n) {
;             const f32x4 v = acc[ai][bj][m][n];
;             float4 r; r.x = xi[m][n].x + v[0]; r.y = xi[m][n].y + v[1]; r.z = xi[m][n].z + v[2]; r.w = xi[m][n].w + v[3];
;             *reinterpret_cast<float4*>(xout + (size_t)ACC_ROW * 2048 + ACC_COL) = r;
;           }
;         EPI_SCHED;
;       }
	v_pk_add_f32 v[94:95], v[94:95], v[180:181]
	v_pk_add_f32 v[96:97], v[96:97], v[182:183]
	global_store_dwordx4 v[140:141], v[94:97], off offset:512
	v_pk_add_f32 v[90:91], v[90:91], v[184:185]
	v_pk_add_f32 v[92:93], v[92:93], v[186:187]
	global_store_dwordx4 v[140:141], v[90:93], off offset:576
	v_pk_add_f32 v[86:87], v[86:87], v[188:189]
	v_pk_add_f32 v[88:89], v[88:89], v[190:191]
	global_store_dwordx4 v[138:139], v[86:89], off offset:512
	v_pk_add_f32 v[82:83], v[82:83], v[192:193]
	v_pk_add_f32 v[84:85], v[84:85], v[194:195]
	global_store_dwordx4 v[138:139], v[82:85], off offset:576
	v_pk_add_f32 v[78:79], v[78:79], v[196:197]
	v_pk_add_f32 v[80:81], v[80:81], v[198:199]
	global_store_dwordx4 v[136:137], v[78:81], off offset:512
	v_pk_add_f32 v[74:75], v[74:75], v[200:201]
	v_pk_add_f32 v[76:77], v[76:77], v[202:203]
	global_store_dwordx4 v[136:137], v[74:77], off offset:576
	v_pk_add_f32 v[70:71], v[70:71], v[204:205]
	v_pk_add_f32 v[72:73], v[72:73], v[206:207]
	global_store_dwordx4 v[134:135], v[70:73], off offset:512
	v_pk_add_f32 v[66:67], v[66:67], v[208:209]
	v_pk_add_f32 v[68:69], v[68:69], v[210:211]
	global_store_dwordx4 v[134:135], v[66:69], off offset:576
	s_nop 1
	v_add_u32_e32 v66, 0x80, v130
	v_ashrrev_i32_e32 v67, 31, v66
	v_lshlrev_b64 v[66:67], 13, v[66:67]
	v_lshl_add_u64 v[66:67], s[72:73], 0, v[66:67]
	v_lshl_add_u64 v[72:73], v[66:67], 0, v[132:133]
	v_add_u32_e32 v66, 0x90, v130
	v_ashrrev_i32_e32 v67, 31, v66
	v_lshlrev_b64 v[66:67], 13, v[66:67]
	v_lshl_add_u64 v[66:67], s[72:73], 0, v[66:67]
	v_lshl_add_u64 v[70:71], v[66:67], 0, v[132:133]
	v_add_u32_e32 v66, 0xa0, v130
	v_ashrrev_i32_e32 v67, 31, v66
	v_lshlrev_b64 v[66:67], 13, v[66:67]
	v_lshl_add_u64 v[66:67], s[72:73], 0, v[66:67]
	v_lshl_add_u64 v[68:69], v[66:67], 0, v[132:133]
	v_add_u32_e32 v66, 0xb0, v130
	v_ashrrev_i32_e32 v67, 31, v66
	v_lshlrev_b64 v[66:67], 13, v[66:67]
	v_lshl_add_u64 v[66:67], s[72:73], 0, v[66:67]
	v_lshl_add_u64 v[66:67], v[66:67], 0, v[132:133]
	global_load_dwordx4 v[180:183], v[72:73], off
	global_load_dwordx4 v[184:187], v[72:73], off offset:64
	global_load_dwordx4 v[188:191], v[70:71], off
	global_load_dwordx4 v[192:195], v[70:71], off offset:64
	global_load_dwordx4 v[196:199], v[68:69], off
	global_load_dwordx4 v[200:203], v[68:69], off offset:64
	global_load_dwordx4 v[204:207], v[66:67], off
	global_load_dwordx4 v[208:211], v[66:67], off offset:64
	s_waitcnt vmcnt(0)
	v_pk_add_f32 v[62:63], v[62:63], v[180:181]
	v_pk_add_f32 v[64:65], v[64:65], v[182:183]
	global_store_dwordx4 v[72:73], v[62:65], off
	v_pk_add_f32 v[58:59], v[58:59], v[184:185]
	v_pk_add_f32 v[60:61], v[60:61], v[186:187]
	global_store_dwordx4 v[72:73], v[58:61], off offset:64
	v_pk_add_f32 v[54:55], v[54:55], v[188:189]
	v_pk_add_f32 v[56:57], v[56:57], v[190:191]
	global_store_dwordx4 v[70:71], v[54:57], off
	v_pk_add_f32 v[50:51], v[50:51], v[192:193]
	v_pk_add_f32 v[52:53], v[52:53], v[194:195]
	global_store_dwordx4 v[70:71], v[50:53], off offset:64
	v_pk_add_f32 v[46:47], v[46:47], v[196:197]
	v_pk_add_f32 v[48:49], v[48:49], v[198:199]
	global_store_dwordx4 v[68:69], v[46:49], off
	v_pk_add_f32 v[42:43], v[42:43], v[200:201]
	v_pk_add_f32 v[44:45], v[44:45], v[202:203]
	global_store_dwordx4 v[68:69], v[42:45], off offset:64
	v_pk_add_f32 v[38:39], v[38:39], v[204:205]
	v_pk_add_f32 v[40:41], v[40:41], v[206:207]
	global_store_dwordx4 v[66:67], v[38:41], off
	v_pk_add_f32 v[34:35], v[34:35], v[208:209]
	v_pk_add_f32 v[36:37], v[36:37], v[210:211]
	global_store_dwordx4 v[66:67], v[34:37], off offset:64
	global_load_dwordx4 v[180:183], v[72:73], off offset:512
	global_load_dwordx4 v[184:187], v[72:73], off offset:576
	global_load_dwordx4 v[188:191], v[70:71], off offset:512
	global_load_dwordx4 v[192:195], v[70:71], off offset:576
	global_load_dwordx4 v[196:199], v[68:69], off offset:512
	global_load_dwordx4 v[200:203], v[68:69], off offset:576
	global_load_dwordx4 v[204:207], v[66:67], off offset:512
	global_load_dwordx4 v[208:211], v[66:67], off offset:576
	s_waitcnt vmcnt(0)
	v_pk_add_f32 v[30:31], v[30:31], v[180:181]
	v_pk_add_f32 v[32:33], v[32:33], v[182:183]
	global_store_dwordx4 v[72:73], v[30:33], off offset:512
	v_pk_add_f32 v[26:27], v[26:27], v[184:185]
	v_pk_add_f32 v[28:29], v[28:29], v[186:187]
	global_store_dwordx4 v[72:73], v[26:29], off offset:576
	v_pk_add_f32 v[22:23], v[22:23], v[188:189]
	v_pk_add_f32 v[24:25], v[24:25], v[190:191]
	global_store_dwordx4 v[70:71], v[22:25], off offset:512
	v_pk_add_f32 v[18:19], v[18:19], v[192:193]
	v_pk_add_f32 v[20:21], v[20:21], v[194:195]
	global_store_dwordx4 v[70:71], v[18:21], off offset:576
	v_pk_add_f32 v[14:15], v[14:15], v[196:197]
	v_pk_add_f32 v[16:17], v[16:17], v[198:199]
	global_store_dwordx4 v[68:69], v[14:17], off offset:512
	v_pk_add_f32 v[10:11], v[10:11], v[200:201]
	v_pk_add_f32 v[12:13], v[12:13], v[202:203]
	global_store_dwordx4 v[68:69], v[10:13], off offset:576
	v_pk_add_f32 v[6:7], v[6:7], v[204:205]
	v_pk_add_f32 v[8:9], v[8:9], v[206:207]
	global_store_dwordx4 v[66:67], v[6:9], off offset:512
	v_pk_add_f32 v[2:3], v[2:3], v[208:209]
	v_pk_add_f32 v[4:5], v[4:5], v[210:211]
	global_store_dwordx4 v[66:67], v[2:5], off offset:576
	s_and_b64 vcc, exec, s[0:1]
	s_mov_b32 s8, s5
	s_mov_b32 s7, s6
	s_cbranch_vccz .LBB0_29
	s_waitcnt vmcnt(0)
	s_movk_i32 s0, 0x100
	v_cmp_gt_u32_e32 vcc, s0, v239
	s_and_saveexec_b64 s[0:1], vcc
	s_cbranch_execz .LBB0_36
	s_barrier

.LBB0_132:
	v_or_b32_e32 v131, 0x10000, v167
	v_add_u32_e32 v136, 0x10400, v167
	v_add_u32_e32 v140, 0x10800, v167
	v_add_u32_e32 v144, 0x10c00, v167
	s_add_i32 s11, s10, 2
	ds_read_b128 v[132:135], v131
	ds_read_b128 v[136:139], v136
	ds_read_b128 v[140:143], v140
	ds_read_b128 v[144:147], v144
	s_cmp_lt_u32 s10, 30
	s_cselect_b32 s12, s8, s5
	s_cselect_b32 s13, s7, s6
	s_cselect_b32 s14, s9, 0
	s_lshl_b32 s13, s13, 11
	s_lshl_b32 s12, s12, 11
	s_or_b32 s15, s14, 64
	s_add_i32 s17, s12, s14
	s_or_b32 s18, s13, 0x40000
	s_add_i32 s16, s13, s14
	s_add_i32 s13, s15, s13
	s_add_i32 s12, s15, s12
	s_lshl_b32 s17, s17, 1
	s_add_i32 s19, s18, s14
	s_add_i32 s18, s18, s15
	s_addk_i32 s9, 0x80
	s_lshl_b32 s16, s16, 1
	s_lshl_b32 s14, s13, 1
	s_lshl_b32 s13, s12, 1
	s_lshl_b32 s15, s19, 1
	s_add_i32 s19, s17, 0x80000
	s_lshl_b32 s12, s18, 1
	s_cmp_gt_u32 s10, 29
	v_add_u32_e32 v148, 0xc000, v0
	v_add_u32_e32 v131, 0xfffc0000, v130
	v_readfirstlane_b32 s10, v148
	s_mov_b32 m0, s10
	ds_read_b128 v[170:173], v166
	ds_read_b128 v[174:177], v166 offset:1024
	ds_read_b128 v[180:183], v166 offset:2048
	ds_read_b128 v[184:187], v166 offset:3072
	ds_read_b128 v[188:191], v166 offset:4096
	ds_read_b128 v[192:195], v166 offset:5120
	ds_read_b128 v[196:199], v166 offset:6144
	ds_read_b128 v[200:203], v166 offset:7168
	global_load_lds_dwordx4 v131, s[86:87]
	v_add_u32_e32 v131, 0xe000, v0
	s_nop 0
	v_readfirstlane_b32 s10, v131
	s_mov_b32 m0, s10
	s_nop 0
	global_load_lds_dwordx4 v130, s[86:87]
	s_waitcnt lgkmcnt(8)
	s_barrier
	s_waitcnt lgkmcnt(0)
	s_setprio 1
	s_waitcnt lgkmcnt(0)
	v_mfma_f32_16x16x32_bf16 v[98:101], v[132:135], v[170:173], v[98:101]
	v_mfma_f32_16x16x32_bf16 v[102:105], v[140:143], v[170:173], v[102:105]
	v_mfma_f32_16x16x32_bf16 v[126:129], v[132:135], v[180:183], v[126:129]
	v_mfma_f32_16x16x32_bf16 v[122:125], v[140:143], v[180:183], v[122:125]
	v_mfma_f32_16x16x32_bf16 v[118:121], v[132:135], v[188:191], v[118:121]
	v_mfma_f32_16x16x32_bf16 v[114:117], v[140:143], v[188:191], v[114:117]
	v_mfma_f32_16x16x32_bf16 v[110:113], v[132:135], v[196:199], v[110:113]
	v_mfma_f32_16x16x32_bf16 v[106:109], v[140:143], v[196:199], v[106:109]
	v_mfma_f32_16x16x32_bf16 v[98:101], v[136:139], v[174:177], v[98:101]
	v_mfma_f32_16x16x32_bf16 v[102:105], v[144:147], v[174:177], v[102:105]
	v_mfma_f32_16x16x32_bf16 v[126:129], v[136:139], v[184:187], v[126:129]
	v_mfma_f32_16x16x32_bf16 v[122:125], v[144:147], v[184:187], v[122:125]
	v_mfma_f32_16x16x32_bf16 v[118:121], v[136:139], v[192:195], v[118:121]
	v_mfma_f32_16x16x32_bf16 v[114:117], v[144:147], v[192:195], v[114:117]
	v_mfma_f32_16x16x32_bf16 v[110:113], v[136:139], v[200:203], v[110:113]
	v_mfma_f32_16x16x32_bf16 v[106:109], v[144:147], v[200:203], v[106:109]
	s_setprio 0
	s_barrier
	v_or_b32_e32 v131, 0x14000, v167
	v_add_u32_e32 v148, 0x14400, v167
	ds_read_b128 v[204:207], v131
	ds_read_b128 v[208:211], v148
	v_add_u32_e32 v131, 0x14800, v167
	v_readfirstlane_b32 s10, v152
	v_add_u32_e32 v148, 0x14c00, v167
	ds_read_b128 v[212:215], v131
	ds_read_b128 v[216:219], v148
	v_add_u32_e32 v131, s16, v150
	s_mov_b32 m0, s10
	v_readfirstlane_b32 s10, v153
	global_load_lds_dwordx4 v131, s[88:89]
	v_add_u32_e32 v131, s16, v151
	s_mov_b32 m0, s10
	s_nop 0
	global_load_lds_dwordx4 v131, s[88:89]
	s_barrier
	s_waitcnt lgkmcnt(0)
	s_setprio 1
	s_waitcnt lgkmcnt(0)
	v_mfma_f32_16x16x32_bf16 v[66:69], v[204:207], v[170:173], v[66:69]
	v_mfma_f32_16x16x32_bf16 v[70:73], v[212:215], v[170:173], v[70:73]
	v_mfma_f32_16x16x32_bf16 v[74:77], v[204:207], v[180:183], v[74:77]
	v_mfma_f32_16x16x32_bf16 v[78:81], v[212:215], v[180:183], v[78:81]
	v_mfma_f32_16x16x32_bf16 v[82:85], v[204:207], v[188:191], v[82:85]
	v_mfma_f32_16x16x32_bf16 v[86:89], v[212:215], v[188:191], v[86:89]
	v_mfma_f32_16x16x32_bf16 v[90:93], v[204:207], v[196:199], v[90:93]
	v_mfma_f32_16x16x32_bf16 v[94:97], v[212:215], v[196:199], v[94:97]
	v_mfma_f32_16x16x32_bf16 v[66:69], v[208:211], v[174:177], v[66:69]
	v_mfma_f32_16x16x32_bf16 v[70:73], v[216:219], v[174:177], v[70:73]
	v_mfma_f32_16x16x32_bf16 v[74:77], v[208:211], v[184:187], v[74:77]
	v_mfma_f32_16x16x32_bf16 v[78:81], v[216:219], v[184:187], v[78:81]
	v_mfma_f32_16x16x32_bf16 v[82:85], v[208:211], v[192:195], v[82:85]
	v_mfma_f32_16x16x32_bf16 v[86:89], v[216:219], v[192:195], v[86:89]
	v_mfma_f32_16x16x32_bf16 v[90:93], v[208:211], v[200:203], v[90:93]
	v_mfma_f32_16x16x32_bf16 v[94:97], v[216:219], v[200:203], v[94:97]
	s_setprio 0
	v_readfirstlane_b32 s10, v0
	v_add_u32_e32 v131, s17, v150
	s_mov_b32 m0, s10
	v_readfirstlane_b32 s10, v154
	s_barrier
	ds_read_b128 v[170:173], v166 offset:16384
	ds_read_b128 v[174:177], v166 offset:17408
	ds_read_b128 v[180:183], v166 offset:18432
	ds_read_b128 v[184:187], v166 offset:19456
	ds_read_b128 v[188:191], v166 offset:20480
	ds_read_b128 v[192:195], v166 offset:21504
	ds_read_b128 v[196:199], v166 offset:22528
	ds_read_b128 v[200:203], v166 offset:23552
	global_load_lds_dwordx4 v131, s[86:87]
	v_add_u32_e32 v131, s17, v151
	s_mov_b32 m0, s10
	s_nop 0
	global_load_lds_dwordx4 v131, s[86:87]
	s_barrier
	s_waitcnt lgkmcnt(0)
	s_setprio 1
	s_waitcnt lgkmcnt(0)
	v_mfma_f32_16x16x32_bf16 v[34:37], v[132:135], v[170:173], v[34:37]
	v_mfma_f32_16x16x32_bf16 v[38:41], v[140:143], v[170:173], v[38:41]
	v_mfma_f32_16x16x32_bf16 v[42:45], v[132:135], v[180:183], v[42:45]
	v_mfma_f32_16x16x32_bf16 v[46:49], v[140:143], v[180:183], v[46:49]
	v_mfma_f32_16x16x32_bf16 v[50:53], v[132:135], v[188:191], v[50:53]
	v_mfma_f32_16x16x32_bf16 v[54:57], v[140:143], v[188:191], v[54:57]
	v_mfma_f32_16x16x32_bf16 v[58:61], v[132:135], v[196:199], v[58:61]
	v_mfma_f32_16x16x32_bf16 v[62:65], v[140:143], v[196:199], v[62:65]
	v_mfma_f32_16x16x32_bf16 v[34:37], v[136:139], v[174:177], v[34:37]
	v_mfma_f32_16x16x32_bf16 v[38:41], v[144:147], v[174:177], v[38:41]
	v_mfma_f32_16x16x32_bf16 v[42:45], v[136:139], v[184:187], v[42:45]
	v_mfma_f32_16x16x32_bf16 v[46:49], v[144:147], v[184:187], v[46:49]
	v_mfma_f32_16x16x32_bf16 v[50:53], v[136:139], v[192:195], v[50:53]
	v_mfma_f32_16x16x32_bf16 v[54:57], v[144:147], v[192:195], v[54:57]
	v_mfma_f32_16x16x32_bf16 v[58:61], v[136:139], v[200:203], v[58:61]
	v_mfma_f32_16x16x32_bf16 v[62:65], v[144:147], v[200:203], v[62:65]
	s_setprio 0
	s_barrier
	v_readfirstlane_b32 s10, v155
	v_add_u32_e32 v131, s15, v150
	s_mov_b32 m0, s10
	v_readfirstlane_b32 s10, v156
	global_load_lds_dwordx4 v131, s[88:89]
	v_add_u32_e32 v131, s15, v151
	s_mov_b32 m0, s10
	s_nop 0
	global_load_lds_dwordx4 v131, s[88:89]
	s_waitcnt vmcnt(6)
	s_barrier
	s_setprio 1
	v_mfma_f32_16x16x32_bf16 v[2:5], v[204:207], v[170:173], v[2:5]
	v_mfma_f32_16x16x32_bf16 v[6:9], v[212:215], v[170:173], v[6:9]
	v_mfma_f32_16x16x32_bf16 v[10:13], v[204:207], v[180:183], v[10:13]
	v_mfma_f32_16x16x32_bf16 v[14:17], v[212:215], v[180:183], v[14:17]
	v_mfma_f32_16x16x32_bf16 v[18:21], v[204:207], v[188:191], v[18:21]
	v_mfma_f32_16x16x32_bf16 v[22:25], v[212:215], v[188:191], v[22:25]
	v_mfma_f32_16x16x32_bf16 v[26:29], v[204:207], v[196:199], v[26:29]
	v_mfma_f32_16x16x32_bf16 v[30:33], v[212:215], v[196:199], v[30:33]
	v_mfma_f32_16x16x32_bf16 v[2:5], v[208:211], v[174:177], v[2:5]
	v_mfma_f32_16x16x32_bf16 v[6:9], v[216:219], v[174:177], v[6:9]
	v_mfma_f32_16x16x32_bf16 v[10:13], v[208:211], v[184:187], v[10:13]
	v_mfma_f32_16x16x32_bf16 v[14:17], v[216:219], v[184:187], v[14:17]
	v_mfma_f32_16x16x32_bf16 v[18:21], v[208:211], v[192:195], v[18:21]
	v_mfma_f32_16x16x32_bf16 v[22:25], v[216:219], v[192:195], v[22:25]
	v_mfma_f32_16x16x32_bf16 v[26:29], v[208:211], v[200:203], v[26:29]
	v_mfma_f32_16x16x32_bf16 v[30:33], v[216:219], v[200:203], v[30:33]
	s_setprio 0
	v_or_b32_e32 v131, 0x18000, v167
	v_add_u32_e32 v136, 0x18400, v167
	s_barrier
	ds_read_b128 v[132:135], v131
	ds_read_b128 v[136:139], v136
	v_add_u32_e32 v131, 0x18800, v167
	v_add_u32_e32 v144, 0x18c00, v167
	ds_read_b128 v[140:143], v131
	ds_read_b128 v[144:147], v144
	v_readfirstlane_b32 s10, v157
	v_add_u32_e32 v131, s19, v150
	s_mov_b32 m0, s10
	v_readfirstlane_b32 s10, v158
	ds_read_b128 v[170:173], v166 offset:32768
	ds_read_b128 v[174:177], v166 offset:33792
	ds_read_b128 v[180:183], v166 offset:34816
	ds_read_b128 v[184:187], v166 offset:35840
	ds_read_b128 v[188:191], v166 offset:36864
	ds_read_b128 v[192:195], v166 offset:37888
	ds_read_b128 v[196:199], v166 offset:38912
	ds_read_b128 v[200:203], v166 offset:39936
	global_load_lds_dwordx4 v131, s[86:87]
	v_add_u32_e32 v131, s19, v151
	s_mov_b32 m0, s10
	s_nop 0
	global_load_lds_dwordx4 v131, s[86:87]
	s_waitcnt lgkmcnt(8)
	s_barrier
	s_waitcnt lgkmcnt(0)
	s_setprio 1
	s_waitcnt lgkmcnt(0)
	v_mfma_f32_16x16x32_bf16 v[98:101], v[132:135], v[170:173], v[98:101]
	v_mfma_f32_16x16x32_bf16 v[102:105], v[140:143], v[170:173], v[102:105]
	v_mfma_f32_16x16x32_bf16 v[126:129], v[132:135], v[180:183], v[126:129]
	v_mfma_f32_16x16x32_bf16 v[122:125], v[140:143], v[180:183], v[122:125]
	v_mfma_f32_16x16x32_bf16 v[118:121], v[132:135], v[188:191], v[118:121]
	v_mfma_f32_16x16x32_bf16 v[114:117], v[140:143], v[188:191], v[114:117]
	v_mfma_f32_16x16x32_bf16 v[110:113], v[132:135], v[196:199], v[110:113]
	v_mfma_f32_16x16x32_bf16 v[106:109], v[140:143], v[196:199], v[106:109]
	v_mfma_f32_16x16x32_bf16 v[98:101], v[136:139], v[174:177], v[98:101]
	v_mfma_f32_16x16x32_bf16 v[102:105], v[144:147], v[174:177], v[102:105]
	v_mfma_f32_16x16x32_bf16 v[126:129], v[136:139], v[184:187], v[126:129]
	v_mfma_f32_16x16x32_bf16 v[122:125], v[144:147], v[184:187], v[122:125]
	v_mfma_f32_16x16x32_bf16 v[118:121], v[136:139], v[192:195], v[118:121]
	v_mfma_f32_16x16x32_bf16 v[114:117], v[144:147], v[192:195], v[114:117]
	v_mfma_f32_16x16x32_bf16 v[110:113], v[136:139], v[200:203], v[110:113]
	v_mfma_f32_16x16x32_bf16 v[106:109], v[144:147], v[200:203], v[106:109]
	s_setprio 0
	s_barrier
	v_or_b32_e32 v131, 0x1c000, v167
	v_add_u32_e32 v148, 0x1c400, v167
	ds_read_b128 v[204:207], v131
	ds_read_b128 v[208:211], v148
	v_add_u32_e32 v131, 0x1c800, v167
	v_readfirstlane_b32 s10, v159
	v_add_u32_e32 v148, 0x1cc00, v167
	ds_read_b128 v[212:215], v131
	ds_read_b128 v[216:219], v148
	v_add_u32_e32 v131, s14, v150
	s_mov_b32 m0, s10
	v_readfirstlane_b32 s10, v160
	global_load_lds_dwordx4 v131, s[88:89]
	v_add_u32_e32 v131, s14, v151
	s_mov_b32 m0, s10
	s_nop 0
	global_load_lds_dwordx4 v131, s[88:89]
	s_barrier
	s_waitcnt lgkmcnt(0)
	s_setprio 1
	s_waitcnt lgkmcnt(0)
	v_mfma_f32_16x16x32_bf16 v[66:69], v[204:207], v[170:173], v[66:69]
	v_mfma_f32_16x16x32_bf16 v[70:73], v[212:215], v[170:173], v[70:73]
	v_mfma_f32_16x16x32_bf16 v[74:77], v[204:207], v[180:183], v[74:77]
	v_mfma_f32_16x16x32_bf16 v[78:81], v[212:215], v[180:183], v[78:81]
	v_mfma_f32_16x16x32_bf16 v[82:85], v[204:207], v[188:191], v[82:85]
	v_mfma_f32_16x16x32_bf16 v[86:89], v[212:215], v[188:191], v[86:89]
	v_mfma_f32_16x16x32_bf16 v[90:93], v[204:207], v[196:199], v[90:93]
	v_mfma_f32_16x16x32_bf16 v[94:97], v[212:215], v[196:199], v[94:97]
	v_mfma_f32_16x16x32_bf16 v[66:69], v[208:211], v[174:177], v[66:69]
	v_mfma_f32_16x16x32_bf16 v[70:73], v[216:219], v[174:177], v[70:73]
	v_mfma_f32_16x16x32_bf16 v[74:77], v[208:211], v[184:187], v[74:77]
	v_mfma_f32_16x16x32_bf16 v[78:81], v[216:219], v[184:187], v[78:81]
	v_mfma_f32_16x16x32_bf16 v[82:85], v[208:211], v[192:195], v[82:85]
	v_mfma_f32_16x16x32_bf16 v[86:89], v[216:219], v[192:195], v[86:89]
	v_mfma_f32_16x16x32_bf16 v[90:93], v[208:211], v[200:203], v[90:93]
	v_mfma_f32_16x16x32_bf16 v[94:97], v[216:219], v[200:203], v[94:97]
	s_setprio 0
	v_readfirstlane_b32 s10, v161
	v_add_u32_e32 v131, s13, v150
	s_mov_b32 m0, s10
	v_readfirstlane_b32 s10, v162
	s_barrier
	ds_read_b128 v[170:173], v166 offset:49152
	ds_read_b128 v[174:177], v166 offset:50176
	ds_read_b128 v[180:183], v166 offset:51200
	ds_read_b128 v[184:187], v166 offset:52224
	ds_read_b128 v[188:191], v166 offset:53248
	ds_read_b128 v[192:195], v166 offset:54272
	ds_read_b128 v[196:199], v166 offset:55296
	ds_read_b128 v[200:203], v166 offset:56320
	global_load_lds_dwordx4 v131, s[86:87]
	v_add_u32_e32 v131, s13, v151
	s_mov_b32 m0, s10
	s_nop 0
	global_load_lds_dwordx4 v131, s[86:87]
	s_barrier
	s_waitcnt lgkmcnt(0)
	s_setprio 1
	s_waitcnt lgkmcnt(0)
	v_mfma_f32_16x16x32_bf16 v[34:37], v[132:135], v[170:173], v[34:37]
	v_mfma_f32_16x16x32_bf16 v[38:41], v[140:143], v[170:173], v[38:41]
	v_mfma_f32_16x16x32_bf16 v[42:45], v[132:135], v[180:183], v[42:45]
	v_mfma_f32_16x16x32_bf16 v[46:49], v[140:143], v[180:183], v[46:49]
	v_mfma_f32_16x16x32_bf16 v[50:53], v[132:135], v[188:191], v[50:53]
	v_mfma_f32_16x16x32_bf16 v[54:57], v[140:143], v[188:191], v[54:57]
	v_mfma_f32_16x16x32_bf16 v[58:61], v[132:135], v[196:199], v[58:61]
	v_mfma_f32_16x16x32_bf16 v[62:65], v[140:143], v[196:199], v[62:65]
	v_mfma_f32_16x16x32_bf16 v[34:37], v[136:139], v[174:177], v[34:37]
	v_mfma_f32_16x16x32_bf16 v[38:41], v[144:147], v[174:177], v[38:41]
	v_mfma_f32_16x16x32_bf16 v[42:45], v[136:139], v[184:187], v[42:45]
	v_mfma_f32_16x16x32_bf16 v[46:49], v[144:147], v[184:187], v[46:49]
	v_mfma_f32_16x16x32_bf16 v[50:53], v[136:139], v[192:195], v[50:53]
	v_mfma_f32_16x16x32_bf16 v[54:57], v[144:147], v[192:195], v[54:57]
	v_mfma_f32_16x16x32_bf16 v[58:61], v[136:139], v[200:203], v[58:61]
	v_mfma_f32_16x16x32_bf16 v[62:65], v[144:147], v[200:203], v[62:65]
	s_setprio 0
	s_barrier
	v_readfirstlane_b32 s10, v163
	v_add_u32_e32 v131, s12, v150
	s_mov_b32 m0, s10
	v_readfirstlane_b32 s10, v165
	global_load_lds_dwordx4 v131, s[88:89]
	v_add_u32_e32 v131, s12, v151
	s_mov_b32 m0, s10
	s_nop 0
	global_load_lds_dwordx4 v131, s[88:89]
	s_waitcnt vmcnt(6)
	s_barrier
	s_setprio 1
	v_mfma_f32_16x16x32_bf16 v[2:5], v[204:207], v[170:173], v[2:5]
	v_mfma_f32_16x16x32_bf16 v[6:9], v[212:215], v[170:173], v[6:9]
	v_mfma_f32_16x16x32_bf16 v[10:13], v[204:207], v[180:183], v[10:13]
	v_mfma_f32_16x16x32_bf16 v[14:17], v[212:215], v[180:183], v[14:17]
	v_mfma_f32_16x16x32_bf16 v[18:21], v[204:207], v[188:191], v[18:21]
	v_mfma_f32_16x16x32_bf16 v[22:25], v[212:215], v[188:191], v[22:25]
	v_mfma_f32_16x16x32_bf16 v[26:29], v[204:207], v[196:199], v[26:29]
	v_mfma_f32_16x16x32_bf16 v[30:33], v[212:215], v[196:199], v[30:33]
	v_mfma_f32_16x16x32_bf16 v[2:5], v[208:211], v[174:177], v[2:5]
	v_mfma_f32_16x16x32_bf16 v[6:9], v[216:219], v[174:177], v[6:9]
	v_mfma_f32_16x16x32_bf16 v[10:13], v[208:211], v[184:187], v[10:13]
	v_mfma_f32_16x16x32_bf16 v[14:17], v[216:219], v[184:187], v[14:17]
	v_mfma_f32_16x16x32_bf16 v[18:21], v[208:211], v[192:195], v[18:21]
	v_mfma_f32_16x16x32_bf16 v[22:25], v[216:219], v[192:195], v[22:25]
	v_mfma_f32_16x16x32_bf16 v[26:29], v[208:211], v[200:203], v[26:29]
	v_mfma_f32_16x16x32_bf16 v[30:33], v[216:219], v[200:203], v[30:33]
	s_setprio 0
	v_add_u32_e32 v130, 0x100, v130
	s_mov_b32 s10, s11
	s_barrier
	s_cbranch_scc0 .LBB0_132
; #define EPI_SCHED __builtin_amdgcn_sched_barrier(0)
; DI void gemm_resid(const u16* A, const u16* Bt, int K, const float* xin, float* xout, int bid, int nb, int tid) {
;     ...
;     for (int ai = 0; ai < 2; ++ai)
; #pragma unroll
;       for (int bj = 0; bj < 2; ++bj) {
;         float4 xi[4][2];
; #pragma unroll
;         for (int m = 0; m < 4; ++m)
; #pragma unroll
;           for (int n = 0; n < 2; ++n) xi[m][n] = *reinterpret_cast<const float4*>(xin + (size_t)ACC_ROW * 2048 + ACC_COL);
; #pragma unroll
;         for (int m = 0; m < 4; ++m)
; #pragma unroll
;           for (int n = 0; n < 2; ++n) {
;             const f32x4 v = acc[ai][bj][m][n];
;             float4 r; r.x = xi[m][n].x + v[0]; r.y = xi[m][n].y + v[1]; r.z = xi[m][n].z + v[2]; r.w = xi[m][n].w + v[3];
;             *reinterpret_cast<float4*>(xout + (size_t)ACC_ROW * 2048 + ACC_COL) = r;
;           }
;         EPI_SCHED;
;       }
	v_mov_b32_e32 v131, v239
	s_nop 0
	v_ashrrev_i32_e32 v130, 2, v131
	v_and_b32_e32 v130, 0xffffffc0, v130
	v_and_or_b32 v132, v131, 15, s8
	v_add_u32_e32 v130, v132, v130
	v_lshrrev_b32_e32 v132, 1, v131
	v_lshrrev_b32_e32 v131, 2, v131
	v_and_b32_e32 v132, 0x60, v132
	v_and_b32_e32 v131, 12, v131
	v_or3_b32 v132, v132, v131, s7
	v_ashrrev_i32_e32 v131, 31, v130
	v_ashrrev_i32_e32 v133, 31, v132
	v_lshlrev_b64 v[134:135], 13, v[130:131]
	v_lshl_add_u64 v[136:137], s[48:49], 0, v[134:135]
	v_lshlrev_b64 v[132:133], 2, v[132:133]
	v_lshl_add_u64 v[142:143], v[136:137], 0, v[132:133]
	v_or_b32_e32 v136, 16, v130
	v_ashrrev_i32_e32 v137, 31, v136
	v_lshlrev_b64 v[136:137], 13, v[136:137]
	v_lshl_add_u64 v[138:139], s[48:49], 0, v[136:137]
	v_lshl_add_u64 v[144:145], v[138:139], 0, v[132:133]
	v_or_b32_e32 v138, 32, v130
	v_ashrrev_i32_e32 v139, 31, v138
	v_lshlrev_b64 v[170:171], 13, v[138:139]
	v_lshl_add_u64 v[138:139], s[48:49], 0, v[170:171]
	v_lshl_add_u64 v[146:147], v[138:139], 0, v[132:133]
	v_or_b32_e32 v138, 48, v130
	v_ashrrev_i32_e32 v139, 31, v138
	v_lshlrev_b64 v[172:173], 13, v[138:139]
	v_lshl_add_u64 v[134:135], s[72:73], 0, v[134:135]
	v_lshl_add_u64 v[138:139], s[48:49], 0, v[172:173]
	v_lshl_add_u64 v[140:141], v[134:135], 0, v[132:133]
	v_lshl_add_u64 v[134:135], s[72:73], 0, v[136:137]
	v_lshl_add_u64 v[148:149], v[138:139], 0, v[132:133]
	v_lshl_add_u64 v[138:139], v[134:135], 0, v[132:133]
	v_lshl_add_u64 v[134:135], s[72:73], 0, v[170:171]
	v_lshl_add_u64 v[136:137], v[134:135], 0, v[132:133]
	v_lshl_add_u64 v[134:135], s[72:73], 0, v[172:173]
	v_lshl_add_u64 v[134:135], v[134:135], 0, v[132:133]
	global_load_dwordx4 v[180:183], v[148:149], off offset:64
	global_load_dwordx4 v[184:187], v[148:149], off
	global_load_dwordx4 v[188:191], v[146:147], off offset:64
	global_load_dwordx4 v[192:195], v[146:147], off
	global_load_dwordx4 v[196:199], v[144:145], off offset:64
	global_load_dwordx4 v[200:203], v[144:145], off
	global_load_dwordx4 v[204:207], v[142:143], off offset:64
	global_load_dwordx4 v[208:211], v[142:143], off
	s_waitcnt vmcnt(0)
	v_pk_add_f32 v[106:107], v[106:107], v[180:181]
	v_pk_add_f32 v[108:109], v[108:109], v[182:183]
	v_pk_add_f32 v[110:111], v[110:111], v[184:185]
	v_pk_add_f32 v[112:113], v[112:113], v[186:187]
	v_pk_add_f32 v[114:115], v[114:115], v[188:189]
	v_pk_add_f32 v[116:117], v[116:117], v[190:191]
	v_pk_add_f32 v[118:119], v[118:119], v[192:193]
	v_pk_add_f32 v[120:121], v[120:121], v[194:195]
	v_pk_add_f32 v[122:123], v[122:123], v[196:197]
	v_pk_add_f32 v[124:125], v[124:125], v[198:199]
	v_pk_add_f32 v[126:127], v[126:127], v[200:201]
	v_pk_add_f32 v[128:129], v[128:129], v[202:203]
	v_pk_add_f32 v[102:103], v[102:103], v[204:205]
	v_pk_add_f32 v[104:105], v[104:105], v[206:207]
	v_pk_add_f32 v[98:99], v[98:99], v[208:209]
	v_pk_add_f32 v[100:101], v[100:101], v[210:211]
	global_store_dwordx4 v[140:141], v[98:101], off
	global_store_dwordx4 v[140:141], v[102:105], off offset:64
	global_store_dwordx4 v[138:139], v[126:129], off
	global_store_dwordx4 v[138:139], v[122:125], off offset:64
	global_store_dwordx4 v[136:137], v[118:121], off
	global_store_dwordx4 v[136:137], v[114:117], off offset:64
	global_store_dwordx4 v[134:135], v[110:113], off
	global_store_dwordx4 v[134:135], v[106:109], off offset:64
	global_load_dwordx4 v[180:183], v[148:149], off offset:576
	global_load_dwordx4 v[184:187], v[148:149], off offset:512
	global_load_dwordx4 v[188:191], v[146:147], off offset:576
	global_load_dwordx4 v[192:195], v[146:147], off offset:512
	global_load_dwordx4 v[196:199], v[144:145], off offset:576
	global_load_dwordx4 v[200:203], v[144:145], off offset:512
	global_load_dwordx4 v[204:207], v[142:143], off offset:576
	global_load_dwordx4 v[208:211], v[142:143], off offset:512
	s_waitcnt vmcnt(0)
; #define EPI_SCHED __builtin_amdgcn_sched_barrier(0)
; DI void gemm_resid(const u16* A, const u16* Bt, int K, const float* xin, float* xout, int bid, int nb, int tid) {
;     ...
;     for (int ai = 0; ai < 2; ++ai)
; #pragma unroll
;       for (int bj = 0; bj < 2; ++bj) {
;         float4 xi[4][2];
; #pragma unroll
;         for (int m = 0; m < 4; ++m)
; #pragma unroll
;           for (int n = 0; n < 2; ++n) xi[m][n] = *reinterpret_cast<const float4*>(xin + (size_t)ACC_ROW * 2048 + ACC_COL);
; #pragma unroll
;         for (int m = 0; m < 4; ++m)
; #pragma unroll
;           for (int n = 0; n < 2; ++n) {
;             const f32x4 v = acc[ai][bj][m][n];
;             float4 r; r.x = xi[m][n].x + v[0]; r.y = xi[m][n].y + v[1]; r.z = xi[m][n].z + v[2]; r.w = xi[m][n].w + v[3];
;             *reinterpret_cast<float4*>(xout + (size_t)ACC_ROW * 2048 + ACC_COL) = r;
;           }
;         EPI_SCHED;
;       }
	v_pk_add_f32 v[94:95], v[94:95], v[180:181]
	v_pk_add_f32 v[96:97], v[96:97], v[182:183]
	v_pk_add_f32 v[90:91], v[90:91], v[184:185]
	v_pk_add_f32 v[92:93], v[92:93], v[186:187]
	v_pk_add_f32 v[86:87], v[86:87], v[188:189]
	v_pk_add_f32 v[88:89], v[88:89], v[190:191]
	v_pk_add_f32 v[82:83], v[82:83], v[192:193]
	v_pk_add_f32 v[84:85], v[84:85], v[194:195]
	v_pk_add_f32 v[78:79], v[78:79], v[196:197]
	v_pk_add_f32 v[80:81], v[80:81], v[198:199]
	v_pk_add_f32 v[74:75], v[74:75], v[200:201]
	v_pk_add_f32 v[76:77], v[76:77], v[202:203]
	v_pk_add_f32 v[70:71], v[70:71], v[204:205]
	v_pk_add_f32 v[72:73], v[72:73], v[206:207]
	v_pk_add_f32 v[66:67], v[66:67], v[208:209]
	v_pk_add_f32 v[68:69], v[68:69], v[210:211]
	global_store_dwordx4 v[140:141], v[66:69], off offset:512
	global_store_dwordx4 v[140:141], v[70:73], off offset:576
	global_store_dwordx4 v[138:139], v[74:77], off offset:512
	global_store_dwordx4 v[138:139], v[78:81], off offset:576
	global_store_dwordx4 v[136:137], v[82:85], off offset:512
	global_store_dwordx4 v[136:137], v[86:89], off offset:576
	global_store_dwordx4 v[134:135], v[90:93], off offset:512
	global_store_dwordx4 v[134:135], v[94:97], off offset:576
	v_add_u32_e32 v66, 0x80, v130
	v_ashrrev_i32_e32 v67, 31, v66
	v_lshlrev_b64 v[66:67], 13, v[66:67]
	v_lshl_add_u64 v[68:69], s[48:49], 0, v[66:67]
	v_lshl_add_u64 v[74:75], v[68:69], 0, v[132:133]
	v_add_u32_e32 v68, 0x90, v130
	v_ashrrev_i32_e32 v69, 31, v68
	v_lshlrev_b64 v[68:69], 13, v[68:69]
	v_lshl_add_u64 v[70:71], s[48:49], 0, v[68:69]
	v_lshl_add_u64 v[76:77], v[70:71], 0, v[132:133]
	v_add_u32_e32 v70, 0xa0, v130
	v_ashrrev_i32_e32 v71, 31, v70
	v_lshlrev_b64 v[82:83], 13, v[70:71]
	v_lshl_add_u64 v[70:71], s[48:49], 0, v[82:83]
	v_lshl_add_u64 v[78:79], v[70:71], 0, v[132:133]
	v_add_u32_e32 v70, 0xb0, v130
	v_ashrrev_i32_e32 v71, 31, v70
	v_lshlrev_b64 v[84:85], 13, v[70:71]
	v_lshl_add_u64 v[66:67], s[72:73], 0, v[66:67]
	v_lshl_add_u64 v[70:71], s[48:49], 0, v[84:85]
	v_lshl_add_u64 v[72:73], v[66:67], 0, v[132:133]
	v_lshl_add_u64 v[66:67], s[72:73], 0, v[68:69]
	v_lshl_add_u64 v[80:81], v[70:71], 0, v[132:133]
	v_lshl_add_u64 v[70:71], v[66:67], 0, v[132:133]
	v_lshl_add_u64 v[66:67], s[72:73], 0, v[82:83]
	v_lshl_add_u64 v[68:69], v[66:67], 0, v[132:133]
	v_lshl_add_u64 v[66:67], s[72:73], 0, v[84:85]
	v_lshl_add_u64 v[66:67], v[66:67], 0, v[132:133]
	global_load_dwordx4 v[180:183], v[80:81], off offset:64
	global_load_dwordx4 v[184:187], v[80:81], off
	global_load_dwordx4 v[188:191], v[78:79], off offset:64
	global_load_dwordx4 v[192:195], v[78:79], off
	global_load_dwordx4 v[196:199], v[76:77], off offset:64
	global_load_dwordx4 v[200:203], v[76:77], off
	global_load_dwordx4 v[204:207], v[74:75], off offset:64
	global_load_dwordx4 v[208:211], v[74:75], off
	s_waitcnt vmcnt(0)
	v_pk_add_f32 v[62:63], v[62:63], v[180:181]
	v_pk_add_f32 v[64:65], v[64:65], v[182:183]
	v_pk_add_f32 v[58:59], v[58:59], v[184:185]
	v_pk_add_f32 v[60:61], v[60:61], v[186:187]
	v_pk_add_f32 v[54:55], v[54:55], v[188:189]
	v_pk_add_f32 v[56:57], v[56:57], v[190:191]
	v_pk_add_f32 v[50:51], v[50:51], v[192:193]
	v_pk_add_f32 v[52:53], v[52:53], v[194:195]
	v_pk_add_f32 v[46:47], v[46:47], v[196:197]
	v_pk_add_f32 v[48:49], v[48:49], v[198:199]
	v_pk_add_f32 v[42:43], v[42:43], v[200:201]
	v_pk_add_f32 v[44:45], v[44:45], v[202:203]
	v_pk_add_f32 v[38:39], v[38:39], v[204:205]
	v_pk_add_f32 v[40:41], v[40:41], v[206:207]
	v_pk_add_f32 v[34:35], v[34:35], v[208:209]
	v_pk_add_f32 v[36:37], v[36:37], v[210:211]
	global_store_dwordx4 v[72:73], v[34:37], off
	global_store_dwordx4 v[72:73], v[38:41], off offset:64
	global_store_dwordx4 v[70:71], v[42:45], off
	global_store_dwordx4 v[70:71], v[46:49], off offset:64
	global_store_dwordx4 v[68:69], v[50:53], off
	global_store_dwordx4 v[68:69], v[54:57], off offset:64
	global_store_dwordx4 v[66:67], v[58:61], off
	global_store_dwordx4 v[66:67], v[62:65], off offset:64
	global_load_dwordx4 v[180:183], v[80:81], off offset:576
	global_load_dwordx4 v[184:187], v[80:81], off offset:512
	global_load_dwordx4 v[188:191], v[78:79], off offset:576
	global_load_dwordx4 v[192:195], v[78:79], off offset:512
	global_load_dwordx4 v[196:199], v[76:77], off offset:576
	global_load_dwordx4 v[200:203], v[76:77], off offset:512
	global_load_dwordx4 v[204:207], v[74:75], off offset:576
	global_load_dwordx4 v[208:211], v[74:75], off offset:512
	s_waitcnt vmcnt(0)
	v_pk_add_f32 v[30:31], v[30:31], v[180:181]
	v_pk_add_f32 v[32:33], v[32:33], v[182:183]
	v_pk_add_f32 v[26:27], v[26:27], v[184:185]
	v_pk_add_f32 v[28:29], v[28:29], v[186:187]
	v_pk_add_f32 v[22:23], v[22:23], v[188:189]
	v_pk_add_f32 v[24:25], v[24:25], v[190:191]
	v_pk_add_f32 v[18:19], v[18:19], v[192:193]
	v_pk_add_f32 v[20:21], v[20:21], v[194:195]
	v_pk_add_f32 v[14:15], v[14:15], v[196:197]
	v_pk_add_f32 v[16:17], v[16:17], v[198:199]
	v_pk_add_f32 v[10:11], v[10:11], v[200:201]
	v_pk_add_f32 v[12:13], v[12:13], v[202:203]
	v_pk_add_f32 v[6:7], v[6:7], v[204:205]
	v_pk_add_f32 v[8:9], v[8:9], v[206:207]
	v_pk_add_f32 v[2:3], v[2:3], v[208:209]
	v_pk_add_f32 v[4:5], v[4:5], v[210:211]
	global_store_dwordx4 v[72:73], v[2:5], off offset:512
	global_store_dwordx4 v[72:73], v[6:9], off offset:576
	global_store_dwordx4 v[70:71], v[10:13], off offset:512
	global_store_dwordx4 v[70:71], v[14:17], off offset:576
	global_store_dwordx4 v[68:69], v[18:21], off offset:512
	global_store_dwordx4 v[68:69], v[22:25], off offset:576
	global_store_dwordx4 v[66:67], v[26:29], off offset:512
	global_store_dwordx4 v[66:67], v[30:33], off offset:576
	s_and_b64 vcc, exec, s[0:1]
	s_mov_b32 s8, s5
	s_mov_b32 s7, s6
	s_cbranch_vccz .LBB0_129
	s_waitcnt vmcnt(0)
	s_movk_i32 s0, 0x100
	v_cmp_gt_u32_e32 vcc, s0, v239
	s_and_saveexec_b64 s[0:1], vcc
	s_cbranch_execz .LBB0_136
	s_barrier
